# P2a gate logsig: removed the value-preserving denormal-rescale and inf/nan select of the compiled logf (argument is always in [1,2]); bit-identical
# speedup vs baseline: 1.0026x; 1.0003x over previous
; __device__ __forceinline__ float bf2f(unsigned b) { return __uint_as_float(b << 16); }
; __device__ __forceinline__ float logsig(float x) { return fminf(x, 0.f) - __logf(1.f + __expf(-fabsf(x))); }
; __device__ __forceinline__ void gla_sample_item(int nh, const u16* PROJ, u16* MIXIN, const float* wgate, const float* bgate, const float* ggla, const float* state_in, float* state_out, LAS unsigned char* lds) {
;     ...
;     const int e = tid & 127, dq = w >> 1;
;     float S[16];
;     const float* sp = state_in + ((size_t)nh * 64 + dq * 16) * 128 + e;
; #pragma unroll
;     for (int i = 0; i < 16; ++i) S[i] = sp[i * 128];
;     if (tid < 256) {
;         const int t = tid >> 6, d = tid & 63;
;         const u16* pr = PROJ + ((size_t)TP + n * 4 + t) * NPROJ;
;         const u32x4 ga = *(const u32x4*)(pr + C_GLR), gb = *(const u32x4*)(pr + C_GLR + 8);
;         const float* wgp = wgate + h * 64 + d;
;         float logit = bgate[h * 64 + d];
;         logit += bf2f(ga.x & 0xffffu) * wgp[0] + bf2f(ga.x >> 16) * wgp[256] + bf2f(ga.y & 0xffffu) * wgp[512] + bf2f(ga.y >> 16) * wgp[768];
;         logit += bf2f(ga.z & 0xffffu) * wgp[1024] + bf2f(ga.z >> 16) * wgp[1280] + bf2f(ga.w & 0xffffu) * wgp[1536] + bf2f(ga.w >> 16) * wgp[1792];
;         logit += bf2f(gb.x & 0xffffu) * wgp[2048] + bf2f(gb.x >> 16) * wgp[2304] + bf2f(gb.y & 0xffffu) * wgp[2560] + bf2f(gb.y >> 16) * wgp[2816];
;         logit += bf2f(gb.z & 0xffffu) * wgp[3072] + bf2f(gb.z >> 16) * wgp[3328] + bf2f(gb.w & 0xffffu) * wgp[3584] + bf2f(gb.w >> 16) * wgp[3840];
;         AKQ[(t * 3 + 0) * 64 + d] = __expf(logsig(logit) * (1.f / 16.f));
;         AKQ[(t * 3 + 1) * 64 + d] = bf2f(pr[C_K + h * 64 + d]);
;         AKQ[(t * 3 + 2) * 64 + d] = bf2f(pr[C_Q + h * 64 + d]) * 0.125f;
.LBB0_224:
	s_cmpk_gt_i32 s50, 0x1ff
	s_mov_b64 s[78:79], -1
	s_cbranch_scc0 .LBB0_235
	s_cmpk_gt_u32 s50, 0x5ff
	s_cbranch_scc0 .LBB0_231
	v_readfirstlane_b32 s86, v67
	s_ashr_i32 s84, s86, 1
	s_add_i32 s35, s50, 0xfffffa00
	s_lshl_b32 s54, s84, 4
	s_and_b32 s85, s50, 0x1fc
	s_lshl_b32 s6, s35, 6
	s_ashr_i32 s55, s54, 31
	s_add_u32 s80, s54, s6
	s_addc_u32 s81, s55, 0
	s_lshl_b64 s[56:57], s[80:81], 9
	v_lshl_add_u64 v[0:1], v[54:55], 0, s[56:57]
	global_load_dword v21, v[0:1], off
	global_load_dword v20, v[0:1], off offset:512
	global_load_dword v19, v[0:1], off offset:1024
	global_load_dword v18, v[0:1], off offset:1536
	global_load_dword v17, v[0:1], off offset:2048
	global_load_dword v16, v[0:1], off offset:2560
	global_load_dword v14, v[0:1], off offset:3072
	global_load_dword v12, v[0:1], off offset:3584
	v_add_co_u32_e32 v0, vcc, 0x1000, v0
	s_and_b32 s55, s50, 3
	s_nop 0
	v_addc_co_u32_e32 v1, vcc, 0, v1, vcc
	global_load_dword v15, v[0:1], off
	global_load_dword v13, v[0:1], off offset:512
	global_load_dword v11, v[0:1], off offset:1024
	global_load_dword v10, v[0:1], off offset:1536
	global_load_dword v9, v[0:1], off offset:2048
	global_load_dword v8, v[0:1], off offset:2560
	global_load_dword v7, v[0:1], off offset:3072
	global_load_dword v6, v[0:1], off offset:3584
	s_mov_b64 s[82:83], exec
	v_readlane_b32 s56, v237, 16
	v_readlane_b32 s57, v237, 17
	s_and_b64 s[56:57], s[82:83], s[56:57]
	s_mov_b64 exec, s[56:57]
	s_cbranch_execz .LBB0_228
	v_or_b32_e32 v0, s85, v67
	v_mul_u32_u24_e32 v0, 0xb00, v0
	v_lshlrev_b32_e32 v52, 1, v0
	v_lshl_add_u64 v[4:5], s[4:5], 0, v[52:53]
	s_mov_b64 s[56:57], 0x5800c00
	v_add_co_u32_e32 v2, vcc, 0x5800000, v4
	s_lshl_b32 s6, s55, 8
	v_lshl_add_u64 v[0:1], v[4:5], 0, s[56:57]
	v_addc_co_u32_e32 v3, vcc, 0, v5, vcc
	v_lshl_add_u64 v[26:27], v[56:57], 0, s[6:7]
	global_load_dwordx4 v[22:25], v[2:3], off offset:3072
	s_nop 0
	global_load_dwordx4 v[0:3], v[0:1], off offset:16
	v_lshl_or_b32 v30, s55, 6, v128
	global_load_dword v170, v[26:27], off
	global_load_dword v171, v[26:27], off offset:1024
	global_load_dword v172, v[26:27], off offset:2048
	global_load_dword v173, v[26:27], off offset:3072
	v_add_co_u32_e32 v28, vcc, 0x1000, v26
	v_lshlrev_b32_e32 v31, 2, v30
	s_nop 0
	v_addc_co_u32_e32 v29, vcc, 0, v27, vcc
	global_load_dword v174, v[28:29], off
	global_load_dword v175, v[28:29], off offset:1024
	global_load_dword v176, v[28:29], off offset:2048
	global_load_dword v177, v[28:29], off offset:3072
	v_add_co_u32_e32 v28, vcc, 0x2000, v26
	s_nop 1
	v_addc_co_u32_e32 v29, vcc, 0, v27, vcc
	global_load_dword v178, v[28:29], off
	global_load_dword v179, v[28:29], off offset:1024
	global_load_dword v180, v[28:29], off offset:2048
	global_load_dword v181, v[28:29], off offset:3072
	v_add_co_u32_e32 v28, vcc, 0x3000, v26
	s_nop 1
	v_addc_co_u32_e32 v29, vcc, 0, v27, vcc
	global_load_dword v182, v[28:29], off
	global_load_dword v183, v[28:29], off offset:1024
	global_load_dword v184, v[28:29], off offset:2048
	global_load_dword v185, v[28:29], off offset:3072
	global_load_dword v186, v31, s[38:39]
	v_lshlrev_b32_e32 v52, 1, v30
	s_mov_b64 s[56:57], 0x5800000
	v_lshl_add_u64 v[28:29], v[4:5], 0, v[52:53]
	v_lshl_add_u64 v[188:189], v[28:29], 0, s[56:57]
	global_load_ushort v190, v[188:189], off offset:512
	global_load_ushort v191, v[188:189], off
	s_movk_i32 s6, 0x3000
	s_waitcnt vmcnt(0)
	v_lshlrev_b32_e32 v29, 16, v22
	v_and_b32_e32 v22, 0xffff0000, v22
	v_mul_f32_e32 v22, v171, v22
	v_fmac_f32_e32 v22, v170, v29
	v_lshlrev_b32_e32 v29, 16, v23
	v_and_b32_e32 v23, 0xffff0000, v23
	v_fmac_f32_e32 v22, v172, v29
	v_fmac_f32_e32 v22, v173, v23
	v_add_f32_e32 v31, v186, v22
	v_lshlrev_b32_e32 v52, 16, v24
	v_and_b32_e32 v24, 0xffff0000, v24
	v_mul_f32_e32 v24, v175, v24
	v_fmac_f32_e32 v24, v174, v52
	v_lshlrev_b32_e32 v52, 16, v25
	v_and_b32_e32 v25, 0xffff0000, v25
	v_fmac_f32_e32 v24, v176, v52
	v_fmac_f32_e32 v24, v177, v25
	v_add_f32_e32 v22, v31, v24
	v_lshlrev_b32_e32 v23, 16, v0
	v_and_b32_e32 v0, 0xffff0000, v0
	v_mul_f32_e32 v0, v179, v0
	v_fmac_f32_e32 v0, v178, v23
	v_lshlrev_b32_e32 v23, 16, v1
	v_and_b32_e32 v1, 0xffff0000, v1
	v_fmac_f32_e32 v0, v180, v23
	v_fmac_f32_e32 v0, v181, v1
	v_add_f32_e32 v22, v22, v0
	v_lshlrev_b32_e32 v23, 16, v2
	v_and_b32_e32 v2, 0xffff0000, v2
	v_mul_f32_e32 v2, v183, v2
	v_fmac_f32_e32 v2, v182, v23
	v_lshlrev_b32_e32 v23, 16, v3
	v_and_b32_e32 v3, 0xffff0000, v3
	v_fmac_f32_e32 v2, v184, v23
	v_fmac_f32_e32 v2, v185, v3
	v_add_f32_e32 v0, v22, v2
	v_min_f32_e32 v1, 0, v0
	v_mul_f32_e64 v0, |v0|, s20
	v_exp_f32_e32 v0, v0
	s_nop 0
	v_add_f32_e32 v0, 1.0, v0
	v_log_f32_e32 v0, v0
	s_nop 0
	v_mul_f32_e32 v2, 0x3f317217, v0
	v_fma_f32 v2, v0, s8, -v2
	v_fmac_f32_e32 v2, 0x3377d1cf, v0
	v_fmac_f32_e32 v2, 0x3f317217, v0
	v_mov_b32_e32 v0, v2
	v_sub_f32_e32 v0, v1, v0
	v_mul_f32_e32 v0, 0x3d800000, v0
	v_mul_f32_e32 v0, 0x3fb8aa3b, v0
	v_exp_f32_e32 v22, v0
	v_lshlrev_b32_e32 v2, 16, v190
	ds_write2st64_b32 v71, v22, v2 offset1:1
	v_lshlrev_b32_e32 v0, 16, v191
	v_mul_f32_e32 v0, 0x3e000000, v0
	ds_write_b32 v71, v0 offset:512

; #define LAS __attribute__((address_space(3)))
; __device__ __forceinline__ float bf2f(unsigned b) { return __uint_as_float(b << 16); }
; __device__ __forceinline__ float logsig(float x) { return fminf(x, 0.f) - __logf(1.f + __expf(-fabsf(x))); }
; template <int MODE>
; __device__ __forceinline__ void gla_chunk_item(int item, const u16* PROJ, u16* MIXIN, const float* wgate, const float* bgate, const float* ggla, float* GS, float* GDEC, const u16* GSB, LAS unsigned char* lds, GateW& gw_) {
;     ...
;     const int qt_ = tid >> 3, qd_ = (tid & 7) * 8;
;     const int vt_ = tid >> 4, ve_ = (tid & 15) * 8;
;     u32x4 qraw, kraw, vraw0, vraw1, sraw[2];
;     if (MODE == 1) qraw = *(const u32x4*)(PROJ + (row0 + qt_) * NPROJ + C_Q + h * 64 + qd_);
;     kraw = *(const u32x4*)(PROJ + (row0 + qt_) * NPROJ + C_K + h * 64 + qd_);
;     vraw0 = *(const u32x4*)(PROJ + (row0 + vt_) * NPROJ + C_V + h * 128 + ve_);
;     vraw1 = *(const u32x4*)(PROJ + (row0 + 32 + vt_) * NPROJ + C_V + h * 128 + ve_);
;     const unsigned glr = *(const unsigned*)(PROJ + (row0 + seg * 8 + (lane >> 3)) * NPROJ + C_GLR + (lane & 7) * 2);
;     if (MODE == 1) {
; #pragma unroll
;         for (int i = 0; i < 2; ++i) sraw[i] = ((const u32x4*)(GSB + (size_t)item * 8192))[tid + 512 * i];
;     }
;     GLR[(seg * 8 + (lane >> 3)) * 16 + (lane & 7) * 2] = bf2f(glr & 0xffffu);
;     GLR[(seg * 8 + (lane >> 3)) * 16 + (lane & 7) * 2 + 1] = bf2f(glr >> 16);
;     float bl[8], run = 0.f;
; #pragma unroll
;     for (int tt = 0; tt < 8; ++tt) {
;         const LAS f32x4* gp = (const LAS f32x4*)(GLR + (seg * 8 + tt) * 16);
;         float logit = gw_.bgd;
; #pragma unroll
;         for (int r4 = 0; r4 < 4; ++r4) { const f32x4 gv = gp[r4]; logit += gv.x * gw_.wg[4 * r4] + gv.y * gw_.wg[4 * r4 + 1] + gv.z * gw_.wg[4 * r4 + 2] + gv.w * gw_.wg[4 * r4 + 3]; }
;         run += logsig(logit) * (1.f / 16.f); bl[tt] = run;
;     }
;     SEG[seg * 64 + d] = run;
.LBB0_244:
	s_add_i32 s6, s50, 0xfffffe00
	s_lshl_b32 s58, s6, 4
	s_lshl_b32 s59, s6, 6
	s_and_b32 s58, s58, 0x3800
	s_and_b32 s59, s59, 0x7c0
	s_or_b32 s60, s58, s59
	v_add_u32_e32 v0, s60, v107
	v_mul_u32_u24_e32 v0, 0xb00, v0
	v_lshlrev_b32_e32 v52, 1, v0
	s_lshr_b32 s54, s55, 6
	v_lshl_add_u64 v[0:1], s[4:5], 0, v[52:53]
	s_lshl_b32 s58, s57, 1
	s_mov_b32 s59, s7
	v_or_b32_e32 v4, s60, v32
	v_mov_b64_e32 v[8:9], s[4:5]
	v_add_u32_e32 v10, s60, v108
	v_lshl_add_u64 v[0:1], v[0:1], 0, s[58:59]
	v_mad_u64_u32 v[4:5], s[58:59], v4, s30, v[8:9]
	s_lshl_b32 s56, s56, 8
	s_mov_b32 s57, s7
	v_mad_u64_u32 v[8:9], s[58:59], v10, s30, v[8:9]
	s_lshl_b32 s80, s54, 3
	v_lshl_add_u64 v[4:5], v[4:5], 0, s[56:57]
	v_lshlrev_b32_e32 v52, 1, v60
	v_lshl_add_u64 v[8:9], v[8:9], 0, s[56:57]
	s_add_i32 s56, s80, s60
	v_lshl_add_u64 v[4:5], v[4:5], 0, v[52:53]
	v_lshl_add_u64 v[8:9], v[8:9], 0, v[52:53]
	v_or_b32_e32 v52, s56, v34
	v_mad_u64_u32 v[102:103], s[56:57], v52, s30, v[76:77]
	global_load_dwordx4 v[8:11], v[8:9], off offset:1024
	v_mov_b32_e32 v79, v53
	global_load_dword v52, v[102:103], off offset:3072
	v_lshl_add_u64 v[0:1], v[0:1], 0, v[78:79]
	v_or_b32_e32 v79, s80, v34
	s_lshl_b32 s56, s54, 9
	v_lshl_add_u32 v79, v79, 6, v109
	s_add_i32 s56, s97, s56
	global_load_dwordx4 v[0:3], v[0:1], off offset:512
	s_or_b32 s59, s80, 3
	global_load_dwordx4 v[4:7], v[4:5], off offset:1024
	s_or_b32 s60, s80, 4
	s_or_b32 s61, s80, 5
	s_or_b32 s62, s80, 6
	s_waitcnt vmcnt(0)
	v_lshlrev_b32_e32 v102, 16, v52
	v_and_b32_e32 v103, 0xffff0000, v52
	ds_write_b64 v79, v[102:103]
	v_mov_b32_e32 v52, s56
	ds_read_b128 v[102:105], v52
	ds_read_b128 v[156:159], v52 offset:16
	ds_read_b128 v[160:163], v52 offset:32
	ds_read_b128 v[164:167], v52 offset:48
	s_mov_b32 s56, 0x3d800000
	s_waitcnt lgkmcnt(3)
	v_mul_f32_e32 v52, v103, v99
	v_fmac_f32_e32 v52, v102, v97
	v_fmac_f32_e32 v52, v104, v95
	s_waitcnt lgkmcnt(2)
	v_mul_f32_e32 v79, v157, v100
	s_waitcnt lgkmcnt(0)
	v_mov_b32_e32 v103, v164
	v_mov_b32_e32 v164, v161
	v_fmac_f32_e32 v52, v105, v93
	v_fmac_f32_e32 v79, v156, v98
	v_mov_b32_e32 v102, v160
	v_pk_mul_f32 v[104:105], v[164:165], v[18:19]
	v_fmac_f32_e32 v79, v158, v96
	v_pk_fma_f32 v[102:103], v[102:103], v[16:17], v[104:105]
	v_mov_b32_e32 v104, v162
	v_mov_b32_e32 v105, v166
	v_add_f32_e32 v52, v28, v52
	v_fmac_f32_e32 v79, v159, v94
	v_pk_fma_f32 v[102:103], v[104:105], v[14:15], v[102:103]
	v_mov_b32_e32 v166, v163
	v_add_f32_e32 v52, v52, v79
	v_pk_fma_f32 v[102:103], v[166:167], v[12:13], v[102:103]
	s_nop 0
	v_add_f32_e32 v52, v52, v102
	v_add_f32_e32 v52, v52, v103
	v_min_f32_e32 v79, 0, v52
	v_mul_f32_e64 v52, |v52|, s20
	v_exp_f32_e32 v52, v52
	s_nop 0
	v_add_f32_e32 v52, 1.0, v52
	v_log_f32_e32 v52, v52
	s_nop 0
	v_mul_f32_e32 v81, 0x3f317217, v52
	v_fma_f32 v81, v52, s8, -v81
	v_fmac_f32_e32 v81, 0x3377d1cf, v52
	v_fmac_f32_e32 v81, 0x3f317217, v52
	v_mov_b32_e32 v52, v81
	v_sub_f32_e32 v52, v79, v52
	v_fma_f32 v52, v52, s56, 0
	s_or_b32 s56, s80, 1
	s_lshl_b32 s57, s56, 6
	s_add_i32 s57, s97, s57
	v_mov_b32_e32 v79, s57
	ds_read_b128 v[102:105], v79
	ds_read_b128 v[156:159], v79 offset:16
	ds_read_b128 v[160:163], v79 offset:32
	ds_read_b128 v[164:167], v79 offset:48
	s_or_b32 s57, s80, 2
	s_waitcnt lgkmcnt(3)
	v_mul_f32_e32 v79, v99, v103
	v_fmac_f32_e32 v79, v97, v102
	v_fmac_f32_e32 v79, v95, v104
	s_waitcnt lgkmcnt(2)
	v_mul_f32_e32 v81, v100, v157
	s_waitcnt lgkmcnt(0)
	v_mov_b32_e32 v103, v164
	v_mov_b32_e32 v164, v161
	v_fmac_f32_e32 v79, v93, v105
	v_fmac_f32_e32 v81, v98, v156
	v_mov_b32_e32 v102, v160
	v_pk_mul_f32 v[104:105], v[18:19], v[164:165]
	v_fmac_f32_e32 v81, v96, v158
	v_pk_fma_f32 v[102:103], v[16:17], v[102:103], v[104:105]
	v_mov_b32_e32 v104, v162
	v_mov_b32_e32 v105, v166
	v_add_f32_e32 v79, v28, v79
	v_fmac_f32_e32 v81, v94, v159
	v_pk_fma_f32 v[102:103], v[14:15], v[104:105], v[102:103]
	v_mov_b32_e32 v166, v163
	v_add_f32_e32 v79, v79, v81
	v_pk_fma_f32 v[102:103], v[12:13], v[166:167], v[102:103]
	s_lshl_b32 s58, s57, 6
	v_add_f32_e32 v79, v79, v102
	v_add_f32_e32 v79, v79, v103
	v_min_f32_e32 v81, 0, v79
	v_mul_f32_e64 v79, |v79|, s20
	v_exp_f32_e32 v79, v79
	s_add_i32 s58, s97, s58
	v_add_f32_e32 v79, 1.0, v79
	v_log_f32_e32 v79, v79
	s_nop 0
	v_mul_f32_e32 v83, 0x3f317217, v79
	v_fma_f32 v83, v79, s8, -v83
	v_fmac_f32_e32 v83, 0x3377d1cf, v79
	v_fmac_f32_e32 v83, 0x3f317217, v79
	v_mov_b32_e32 v79, v83
	v_sub_f32_e32 v79, v81, v79
	v_mov_b32_e32 v81, s58
	ds_read_b128 v[102:105], v81
	ds_read_b128 v[156:159], v81 offset:16
	ds_read_b128 v[160:163], v81 offset:32
	ds_read_b128 v[164:167], v81 offset:48
	s_lshl_b32 s58, s59, 6
	s_waitcnt lgkmcnt(3)
	v_mov_b32_e32 v168, v102
	s_waitcnt lgkmcnt(2)
	v_mov_b32_e32 v169, v156
	v_mov_b32_e32 v156, v103
	v_pk_mul_f32 v[102:103], v[26:27], v[156:157]
	v_mov_b32_e32 v156, v104
	v_pk_fma_f32 v[102:103], v[24:25], v[168:169], v[102:103]
	v_mov_b32_e32 v157, v158
	v_pk_fma_f32 v[102:103], v[22:23], v[156:157], v[102:103]
	v_mov_b32_e32 v158, v105
	v_pk_fma_f32 v[102:103], v[20:21], v[158:159], v[102:103]
	s_add_i32 s58, s97, s58
	v_add_f32_e32 v81, v28, v102
	v_add_f32_e32 v81, v81, v103
	s_waitcnt lgkmcnt(0)
; #define LAS __attribute__((address_space(3)))
; __device__ __forceinline__ float logsig(float x) { return fminf(x, 0.f) - __logf(1.f + __expf(-fabsf(x))); }
; template <int MODE>
; __device__ __forceinline__ void gla_chunk_item(int item, const u16* PROJ, u16* MIXIN, const float* wgate, const float* bgate, const float* ggla, float* GS, float* GDEC, const u16* GSB, LAS unsigned char* lds, GateW& gw_) {
;     ...
; #pragma unroll
;     for (int tt = 0; tt < 8; ++tt) {
;         const LAS f32x4* gp = (const LAS f32x4*)(GLR + (seg * 8 + tt) * 16);
;         float logit = gw_.bgd;
; #pragma unroll
;         for (int r4 = 0; r4 < 4; ++r4) { const f32x4 gv = gp[r4]; logit += gv.x * gw_.wg[4 * r4] + gv.y * gw_.wg[4 * r4 + 1] + gv.z * gw_.wg[4 * r4 + 2] + gv.w * gw_.wg[4 * r4 + 3]; }
;         run += logsig(logit) * (1.f / 16.f); bl[tt] = run;
;     }
	v_mov_b32_e32 v103, v164
	v_mov_b32_e32 v164, v161
	v_mov_b32_e32 v102, v160
	v_pk_mul_f32 v[104:105], v[18:19], v[164:165]
	v_fmamk_f32 v79, v79, 0x3d800000, v52
	v_pk_fma_f32 v[102:103], v[16:17], v[102:103], v[104:105]
	v_mov_b32_e32 v104, v162
	v_mov_b32_e32 v105, v166
	v_pk_fma_f32 v[102:103], v[14:15], v[104:105], v[102:103]
	v_mov_b32_e32 v166, v163
	v_pk_fma_f32 v[102:103], v[12:13], v[166:167], v[102:103]
	s_nop 0
	v_add_f32_e32 v81, v81, v102
	v_add_f32_e32 v81, v81, v103
	v_min_f32_e32 v83, 0, v81
	v_mul_f32_e64 v81, |v81|, s20
	v_exp_f32_e32 v81, v81
	s_nop 0
	v_add_f32_e32 v81, 1.0, v81
	v_log_f32_e32 v81, v81
	s_nop 0
	v_mul_f32_e32 v85, 0x3f317217, v81
	v_fma_f32 v85, v81, s8, -v85
	v_fmac_f32_e32 v85, 0x3377d1cf, v81
	v_fmac_f32_e32 v85, 0x3f317217, v81
	v_mov_b32_e32 v81, v85
	v_sub_f32_e32 v81, v83, v81
	v_mov_b32_e32 v83, s58
	ds_read_b128 v[102:105], v83
	ds_read_b128 v[156:159], v83 offset:16
	ds_read_b128 v[160:163], v83 offset:32
	ds_read_b128 v[164:167], v83 offset:48
	s_lshl_b32 s58, s60, 6
	s_waitcnt lgkmcnt(3)
	v_mov_b32_e32 v168, v102
	s_waitcnt lgkmcnt(2)
	v_mov_b32_e32 v169, v156
	v_mov_b32_e32 v156, v103
	v_pk_mul_f32 v[102:103], v[26:27], v[156:157]
	v_mov_b32_e32 v156, v104
	v_pk_fma_f32 v[102:103], v[24:25], v[168:169], v[102:103]
	v_mov_b32_e32 v157, v158
	v_pk_fma_f32 v[102:103], v[22:23], v[156:157], v[102:103]
	v_mov_b32_e32 v158, v105
	v_pk_fma_f32 v[102:103], v[20:21], v[158:159], v[102:103]
	s_add_i32 s58, s97, s58
	v_add_f32_e32 v83, v28, v102
	v_add_f32_e32 v83, v83, v103
	s_waitcnt lgkmcnt(0)
	v_mov_b32_e32 v103, v164
	v_mov_b32_e32 v164, v161
	v_mov_b32_e32 v102, v160
	v_pk_mul_f32 v[104:105], v[18:19], v[164:165]
	v_fmamk_f32 v81, v81, 0x3d800000, v79
	v_pk_fma_f32 v[102:103], v[16:17], v[102:103], v[104:105]
	v_mov_b32_e32 v104, v162
	v_mov_b32_e32 v105, v166
	v_pk_fma_f32 v[102:103], v[14:15], v[104:105], v[102:103]
	v_mov_b32_e32 v166, v163
	v_pk_fma_f32 v[102:103], v[12:13], v[166:167], v[102:103]
	s_nop 0
	v_add_f32_e32 v83, v83, v102
	v_add_f32_e32 v83, v83, v103
	v_min_f32_e32 v85, 0, v83
	v_mul_f32_e64 v83, |v83|, s20
	v_exp_f32_e32 v83, v83
	s_nop 0
	v_add_f32_e32 v83, 1.0, v83
	v_log_f32_e32 v83, v83
	s_nop 0
	v_mul_f32_e32 v87, 0x3f317217, v83
	v_fma_f32 v87, v83, s8, -v87
	v_fmac_f32_e32 v87, 0x3377d1cf, v83
	v_fmac_f32_e32 v87, 0x3f317217, v83
	v_mov_b32_e32 v83, v87
	v_sub_f32_e32 v83, v85, v83
	v_mov_b32_e32 v85, s58
	ds_read_b128 v[102:105], v85
	ds_read_b128 v[156:159], v85 offset:16
	ds_read_b128 v[160:163], v85 offset:32
	ds_read_b128 v[164:167], v85 offset:48
	s_lshl_b32 s58, s61, 6
	s_waitcnt lgkmcnt(3)
	v_mov_b32_e32 v168, v102
	s_waitcnt lgkmcnt(2)
	v_mov_b32_e32 v169, v156
	v_mov_b32_e32 v156, v103
	v_pk_mul_f32 v[102:103], v[26:27], v[156:157]
	v_mov_b32_e32 v156, v104
	v_pk_fma_f32 v[102:103], v[24:25], v[168:169], v[102:103]
	v_mov_b32_e32 v157, v158
	v_pk_fma_f32 v[102:103], v[22:23], v[156:157], v[102:103]
	v_mov_b32_e32 v158, v105
	v_pk_fma_f32 v[102:103], v[20:21], v[158:159], v[102:103]
	s_add_i32 s58, s97, s58
	v_add_f32_e32 v85, v28, v102
	v_add_f32_e32 v85, v85, v103
	s_waitcnt lgkmcnt(0)
	v_mov_b32_e32 v103, v164
	v_mov_b32_e32 v164, v161
	v_mov_b32_e32 v102, v160
	v_pk_mul_f32 v[104:105], v[18:19], v[164:165]
	v_fmamk_f32 v83, v83, 0x3d800000, v81
	v_pk_fma_f32 v[102:103], v[16:17], v[102:103], v[104:105]
	v_mov_b32_e32 v104, v162
	v_mov_b32_e32 v105, v166
	v_pk_fma_f32 v[102:103], v[14:15], v[104:105], v[102:103]
	v_mov_b32_e32 v166, v163
	v_pk_fma_f32 v[102:103], v[12:13], v[166:167], v[102:103]
	s_nop 0
	v_add_f32_e32 v85, v85, v102
	v_add_f32_e32 v85, v85, v103
	v_min_f32_e32 v87, 0, v85
	v_mul_f32_e64 v85, |v85|, s20
	v_exp_f32_e32 v85, v85
	s_nop 0
	v_add_f32_e32 v85, 1.0, v85
	v_log_f32_e32 v85, v85
	s_nop 0
	v_mul_f32_e32 v101, 0x3f317217, v85
	v_fma_f32 v101, v85, s8, -v101
	v_fmac_f32_e32 v101, 0x3377d1cf, v85
	v_fmac_f32_e32 v101, 0x3f317217, v85
	v_mov_b32_e32 v85, v101
	v_sub_f32_e32 v85, v87, v85
	v_mov_b32_e32 v87, s58
	ds_read_b128 v[102:105], v87
	ds_read_b128 v[156:159], v87 offset:16
	ds_read_b128 v[160:163], v87 offset:32
	ds_read_b128 v[164:167], v87 offset:48
	s_lshl_b32 s58, s62, 6
	s_waitcnt lgkmcnt(3)
	v_mov_b32_e32 v168, v102
	s_waitcnt lgkmcnt(2)
	v_mov_b32_e32 v169, v156
	v_mov_b32_e32 v156, v103
	v_pk_mul_f32 v[102:103], v[26:27], v[156:157]
	v_mov_b32_e32 v156, v104
	v_pk_fma_f32 v[102:103], v[24:25], v[168:169], v[102:103]
	v_mov_b32_e32 v157, v158
	v_pk_fma_f32 v[102:103], v[22:23], v[156:157], v[102:103]
	v_mov_b32_e32 v158, v105
	v_pk_fma_f32 v[102:103], v[20:21], v[158:159], v[102:103]
	s_add_i32 s58, s97, s58
	v_add_f32_e32 v87, v28, v102
	v_add_f32_e32 v87, v87, v103
	s_waitcnt lgkmcnt(0)
	v_mov_b32_e32 v103, v164
	v_mov_b32_e32 v164, v161
	v_mov_b32_e32 v102, v160
	v_pk_mul_f32 v[104:105], v[18:19], v[164:165]
	v_fmamk_f32 v85, v85, 0x3d800000, v83
	v_pk_fma_f32 v[102:103], v[16:17], v[102:103], v[104:105]
	v_mov_b32_e32 v104, v162
	v_mov_b32_e32 v105, v166
	v_pk_fma_f32 v[102:103], v[14:15], v[104:105], v[102:103]
	v_mov_b32_e32 v166, v163
	v_pk_fma_f32 v[102:103], v[12:13], v[166:167], v[102:103]
	s_nop 0
	v_add_f32_e32 v87, v87, v102
	v_add_f32_e32 v87, v87, v103
	v_min_f32_e32 v101, 0, v87
	v_mul_f32_e64 v87, |v87|, s20
	v_exp_f32_e32 v87, v87
	s_nop 0
	v_add_f32_e32 v87, 1.0, v87
	v_log_f32_e32 v87, v87
	s_nop 0
	v_mul_f32_e32 v102, 0x3f317217, v87
	v_fma_f32 v102, v87, s8, -v102
	v_fmac_f32_e32 v102, 0x3377d1cf, v87
	v_fmac_f32_e32 v102, 0x3f317217, v87
	v_mov_b32_e32 v87, v102
	v_sub_f32_e32 v87, v101, v87
	v_mov_b32_e32 v101, s58
	ds_read_b128 v[102:105], v101
	ds_read_b128 v[156:159], v101 offset:16
	ds_read_b128 v[160:163], v101 offset:32
	ds_read_b128 v[164:167], v101 offset:48
	s_or_b32 s58, s80, 7
	s_waitcnt lgkmcnt(3)
; #define LAS __attribute__((address_space(3)))
; __device__ __forceinline__ float logsig(float x) { return fminf(x, 0.f) - __logf(1.f + __expf(-fabsf(x))); }
; #define LBAR() do { asm volatile("s_waitcnt lgkmcnt(0)" ::: "memory"); __builtin_amdgcn_s_barrier(); asm volatile("" ::: "memory"); } while (0)
; template <int MODE>
; __device__ __forceinline__ void gla_chunk_item(int item, const u16* PROJ, u16* MIXIN, const float* wgate, const float* bgate, const float* ggla, float* GS, float* GDEC, const u16* GSB, LAS unsigned char* lds, GateW& gw_) {
;     ...
; #pragma unroll
;     for (int tt = 0; tt < 8; ++tt) {
;         const LAS f32x4* gp = (const LAS f32x4*)(GLR + (seg * 8 + tt) * 16);
;         float logit = gw_.bgd;
; #pragma unroll
;         for (int r4 = 0; r4 < 4; ++r4) { const f32x4 gv = gp[r4]; logit += gv.x * gw_.wg[4 * r4] + gv.y * gw_.wg[4 * r4 + 1] + gv.z * gw_.wg[4 * r4 + 2] + gv.w * gw_.wg[4 * r4 + 3]; }
;         run += logsig(logit) * (1.f / 16.f); bl[tt] = run;
;     }
;     SEG[seg * 64 + d] = run;
;     if (MODE == 1) *(LAS u32x4*)(RQ + qt_ * 64 + qd_) = qraw;
;     *(LAS u32x4*)(RK + qt_ * 64 + qd_) = kraw;
;     *(LAS u32x2*)(RV + vt_ * RP + ve_) = (u32x2){vraw0.x, vraw0.y}; *(LAS u32x2*)(RV + vt_ * RP + ve_ + 4) = (u32x2){vraw0.z, vraw0.w};
;     *(LAS u32x2*)(RV + (32 + vt_) * RP + ve_) = (u32x2){vraw1.x, vraw1.y}; *(LAS u32x2*)(RV + (32 + vt_) * RP + ve_ + 4) = (u32x2){vraw1.z, vraw1.w};
;     if (MODE == 1) {
; #pragma unroll
;         for (int i = 0; i < 2; ++i) { const int idx = tid + 512 * i; LAS u16* sp_ = SN + (idx >> 4) * RP + (idx & 15) * 8;
;             *(LAS u32x2*)sp_ = (u32x2){sraw[i].x, sraw[i].y}; *(LAS u32x2*)(sp_ + 4) = (u32x2){sraw[i].z, sraw[i].w}; }
;     }
;     LBAR();
	v_mov_b32_e32 v168, v102
	s_waitcnt lgkmcnt(2)
	v_mov_b32_e32 v169, v156
	v_mov_b32_e32 v156, v103
	v_pk_mul_f32 v[26:27], v[26:27], v[156:157]
	s_lshl_b32 s63, s58, 6
	v_pk_fma_f32 v[24:25], v[24:25], v[168:169], v[26:27]
	v_mov_b32_e32 v26, v104
	v_mov_b32_e32 v27, v158
	v_pk_fma_f32 v[22:23], v[22:23], v[26:27], v[24:25]
	v_mov_b32_e32 v158, v105
	v_pk_fma_f32 v[20:21], v[20:21], v[158:159], v[22:23]
	s_add_i32 s63, s97, s63
	v_add_f32_e32 v20, v28, v20
	v_add_f32_e32 v24, v20, v21
	s_waitcnt lgkmcnt(0)
	v_mov_b32_e32 v21, v164
	v_mov_b32_e32 v164, v161
	v_mov_b32_e32 v20, v160
	v_pk_mul_f32 v[22:23], v[18:19], v[164:165]
	v_mov_b32_e32 v155, s63
	v_pk_fma_f32 v[20:21], v[16:17], v[20:21], v[22:23]
	v_mov_b32_e32 v22, v162
	v_mov_b32_e32 v23, v166
	v_pk_fma_f32 v[20:21], v[14:15], v[22:23], v[20:21]
	v_mov_b32_e32 v166, v163
	v_pk_fma_f32 v[20:21], v[12:13], v[166:167], v[20:21]
	v_fmamk_f32 v87, v87, 0x3d800000, v85
	v_add_f32_e32 v20, v24, v20
	v_add_f32_e32 v20, v20, v21
	v_min_f32_e32 v21, 0, v20
	v_mul_f32_e64 v20, |v20|, s20
	v_exp_f32_e32 v20, v20
	s_and_b32 s63, s55, 0x3fffffc0
	s_cmp_gt_u32 s55, 63
	v_add_f32_e32 v20, 1.0, v20
	v_log_f32_e32 v20, v20
	s_nop 0
	v_mul_f32_e32 v22, 0x3f317217, v20
	v_fma_f32 v22, v20, s8, -v22
	v_fmac_f32_e32 v22, 0x3377d1cf, v20
	v_fmac_f32_e32 v22, 0x3f317217, v20
	v_mov_b32_e32 v20, v22
	v_sub_f32_e32 v101, v21, v20
	ds_read_b128 v[20:23], v155
	ds_read_b128 v[24:27], v155 offset:16
	ds_read_b128 v[102:105], v155 offset:32
	ds_read_b128 v[156:159], v155 offset:48
	s_waitcnt lgkmcnt(3)
	v_mul_f32_e32 v21, v99, v21
	v_fmac_f32_e32 v21, v97, v20
	v_fmac_f32_e32 v21, v95, v22
	v_fmac_f32_e32 v21, v93, v23
	v_add_f32_e32 v20, v28, v21
	s_waitcnt lgkmcnt(2)
	v_mul_f32_e32 v21, v100, v25
	v_fmac_f32_e32 v21, v98, v24
	v_fmac_f32_e32 v21, v96, v26
	v_fmac_f32_e32 v21, v94, v27
	v_add_f32_e32 v22, v20, v21
	s_waitcnt lgkmcnt(0)
	v_mov_b32_e32 v21, v156
	v_mov_b32_e32 v156, v103
	v_mov_b32_e32 v20, v102
	v_pk_mul_f32 v[18:19], v[18:19], v[156:157]
	s_nop 0
	v_pk_fma_f32 v[16:17], v[16:17], v[20:21], v[18:19]
	v_mov_b32_e32 v18, v104
	v_mov_b32_e32 v19, v158
	v_pk_fma_f32 v[14:15], v[14:15], v[18:19], v[16:17]
	v_mov_b32_e32 v158, v105
	v_pk_fma_f32 v[12:13], v[12:13], v[158:159], v[14:15]
	v_fmamk_f32 v15, v101, 0x3d800000, v87
	v_add_f32_e32 v12, v22, v12
	v_add_f32_e32 v12, v12, v13
	v_min_f32_e32 v13, 0, v12
	v_mul_f32_e64 v12, |v12|, s20
	v_exp_f32_e32 v12, v12
	v_lshl_add_u32 v16, s54, 10, v112
	v_lshl_add_u32 v17, s56, 7, v112
	v_lshl_add_u32 v18, s57, 7, v112
	v_add_f32_e32 v12, 1.0, v12
	v_cmp_gt_f32_e32 vcc, s21, v12
	v_lshl_add_u32 v19, s59, 7, v112
	v_lshl_add_u32 v20, s60, 7, v112
	v_cndmask_b32_e64 v14, 0, 32, vcc
	v_ldexp_f32 v12, v12, v14
	v_log_f32_e32 v12, v12
	v_lshl_add_u32 v21, s61, 7, v112
	v_lshl_add_u32 v22, s62, 7, v112
	v_mul_f32_e32 v14, 0x3f317217, v12
	v_fma_f32 v14, v12, s8, -v14
	v_fmac_f32_e32 v14, 0x3377d1cf, v12
	v_fmac_f32_e32 v14, 0x3f317217, v12
	v_cmp_lt_f32_e64 s[78:79], |v12|, s9
	s_nop 1
	v_cndmask_b32_e64 v12, v12, v14, s[78:79]
	v_cndmask_b32_e32 v14, 0, v152, vcc
	v_sub_f32_e32 v12, v12, v14
	v_sub_f32_e32 v12, v13, v12
	v_lshl_add_u32 v13, s63, 2, v33
	v_fmamk_f32 v12, v12, 0x3d800000, v15
	ds_write_b32 v13, v12
	ds_write_b128 v110, v[0:3] offset:45056
	v_add_u32_e32 v0, 0xd000, v111
	ds_write2_b64 v0, v[4:5], v[6:7] offset1:1
	v_add_u32_e32 v0, 0xf100, v111
	ds_write2_b64 v0, v[8:9], v[10:11] offset1:1
	s_waitcnt lgkmcnt(0)
	s_barrier
; #define LAS __attribute__((address_space(3)))
; __device__ __forceinline__ float bf2f(unsigned b) { return __uint_as_float(b << 16); }
; __device__ __forceinline__ unsigned pk2(float lo, float hi) { unsigned r; asm("v_cvt_pk_bf16_f32 %0, %1, %2" : "=v"(r) : "v"(lo), "v"(hi)); return r; }
; template <int MODE>
; __device__ __forceinline__ void gla_chunk_item(int item, const u16* PROJ, u16* MIXIN, const float* wgate, const float* bgate, const float* ggla, float* GS, float* GDEC, const u16* GSB, LAS unsigned char* lds, GateW& gw_) {
;     ...
;     float off = 0.f, tot = 0.f;
; #pragma unroll
;     for (int s = 0; s < 8; ++s) { const float v = SEG[s * 64 + d]; tot += v; off += (s < seg) ? v : 0.f; }
;     if (MODE == 0) {
;         float kd[8];
; #pragma unroll
;         for (int tt = 0; tt < 8; ++tt) kd[tt] = bf2f(RK[(seg * 8 + tt) * 64 + d]) * __expf(tot - (off + bl[tt]));
;         u32x4 kk; kk.x = pk2(kd[0], kd[1]); kk.y = pk2(kd[2], kd[3]); kk.z = pk2(kd[4], kd[5]); kk.w = pk2(kd[6], kd[7]);
;         *(LAS u32x4*)(KdT + d * LD + seg * 8) = kk;
;         if (seg == 0) GDEC[(size_t)item * 64 + d] = __expf(tot);
	ds_read2st64_b32 v[0:1], v33 offset1:1
	s_cselect_b64 vcc, -1, 0
	s_cmpk_gt_u32 s55, 0x7f
	s_cselect_b64 s[90:91], -1, 0
	s_cmpk_gt_u32 s55, 0xbf
	s_waitcnt lgkmcnt(0)
	v_add_f32_e32 v0, 0, v0
	v_cndmask_b32_e32 v2, 0, v0, vcc
	v_add_f32_e32 v3, v0, v1
	v_cndmask_b32_e64 v0, 0, v1, s[90:91]
	v_add_f32_e32 v2, v2, v0
	ds_read2st64_b32 v[0:1], v33 offset0:2 offset1:3
	s_cselect_b64 s[88:89], -1, 0
	s_cmpk_gt_u32 s55, 0xff
	s_cselect_b64 s[86:87], -1, 0
	s_cmpk_gt_u32 s55, 0x13f
	s_waitcnt lgkmcnt(0)
	v_add_f32_e32 v3, v3, v0
	v_cndmask_b32_e64 v0, 0, v0, s[88:89]
	v_add_f32_e32 v0, v2, v0
	v_add_f32_e32 v2, v3, v1
	v_cndmask_b32_e64 v1, 0, v1, s[86:87]
	v_add_f32_e32 v3, v0, v1
	ds_read2st64_b32 v[0:1], v33 offset0:4 offset1:5
	s_cselect_b64 s[84:85], -1, 0
	s_cmpk_gt_u32 s55, 0x17f
	s_cselect_b64 s[82:83], -1, 0
	s_cmpk_gt_u32 s55, 0x1bf
	s_waitcnt lgkmcnt(0)
	v_add_f32_e32 v2, v2, v0
	v_cndmask_b32_e64 v0, 0, v0, s[84:85]
	v_add_f32_e32 v0, v3, v0
	v_add_f32_e32 v2, v2, v1
	v_cndmask_b32_e64 v1, 0, v1, s[82:83]
	v_add_f32_e32 v3, v0, v1
	ds_read2st64_b32 v[0:1], v33 offset0:6 offset1:7
	s_cselect_b64 s[80:81], -1, 0
	s_cmpk_gt_u32 s55, 0x1ff
	s_cselect_b64 s[78:79], -1, 0
	s_and_b64 vcc, exec, vcc
	s_waitcnt lgkmcnt(0)
	v_add_f32_e32 v14, v2, v0
	v_cndmask_b32_e64 v0, 0, v0, s[80:81]
	v_add_f32_e32 v0, v3, v0
	v_cndmask_b32_e64 v2, 0, v1, s[78:79]
	v_add_f32_e32 v3, v0, v2
	ds_read_u16 v0, v16 offset:45056
	v_mov_b32_e32 v2, v1
	v_add_f32_e32 v5, v52, v3
	v_add_f32_e32 v6, v81, v3
	v_add_f32_e32 v7, v83, v3
	s_waitcnt lgkmcnt(0)
	v_lshlrev_b32_e32 v4, 16, v0
	v_pk_add_f32 v[0:1], v[14:15], v[2:3]
	v_add_f32_e32 v8, v85, v3
	v_sub_f32_e32 v2, v0, v5
	v_mul_f32_e32 v2, 0x3fb8aa3b, v2
	v_exp_f32_e32 v2, v2
	v_add_f32_e32 v5, v79, v3
	v_sub_f32_e32 v5, v0, v5
	v_mul_f32_e32 v5, 0x3fb8aa3b, v5
	v_mul_f32_e32 v2, v2, v4
	ds_read_u16 v4, v17 offset:45056
	v_exp_f32_e32 v5, v5
	v_sub_f32_e32 v6, v0, v6
	v_mul_f32_e32 v6, 0x3fb8aa3b, v6
	v_exp_f32_e32 v6, v6
	s_waitcnt lgkmcnt(0)
	v_lshlrev_b32_e32 v4, 16, v4
	v_mul_f32_e32 v4, v5, v4
	ds_read_u16 v5, v18 offset:45056
	v_sub_f32_e32 v7, v0, v7
	v_mul_f32_e32 v7, 0x3fb8aa3b, v7
	v_exp_f32_e32 v7, v7
	v_sub_f32_e32 v8, v0, v8
	s_waitcnt lgkmcnt(0)
	v_lshlrev_b32_e32 v5, 16, v5
	v_mul_f32_e32 v5, v6, v5
	ds_read_u16 v6, v19 offset:45056
	v_mul_f32_e32 v8, 0x3fb8aa3b, v8
	v_exp_f32_e32 v8, v8
	v_add_f32_e32 v9, v87, v3
	v_sub_f32_e32 v9, v0, v9
	s_waitcnt lgkmcnt(0)
	v_lshlrev_b32_e32 v6, 16, v6
	v_mul_f32_e32 v6, v7, v6
	ds_read_u16 v7, v20 offset:45056
	v_mul_f32_e32 v9, 0x3fb8aa3b, v9
	v_exp_f32_e32 v9, v9
	v_sub_f32_e32 v1, v0, v1
	v_mul_f32_e32 v1, 0x3fb8aa3b, v1
	s_waitcnt lgkmcnt(0)
	v_lshlrev_b32_e32 v7, 16, v7
	v_mul_f32_e32 v7, v8, v7
	ds_read_u16 v8, v21 offset:45056
	v_exp_f32_e32 v1, v1
	v_add_f32_e32 v3, v12, v3
	v_sub_f32_e32 v3, v0, v3
	v_mul_f32_e32 v3, 0x3fb8aa3b, v3
	s_waitcnt lgkmcnt(0)
	v_lshlrev_b32_e32 v8, 16, v8
	v_mul_f32_e32 v8, v9, v8
	ds_read_u16 v9, v22 offset:45056
	v_exp_f32_e32 v3, v3
	v_cvt_pk_bf16_f32 v2, v2, v4
	v_cvt_pk_bf16_f32 v4, v7, v8
	s_waitcnt lgkmcnt(0)
	v_lshlrev_b32_e32 v9, 16, v9
	v_mul_f32_e32 v1, v1, v9
	v_lshl_add_u32 v9, s58, 7, v112
	ds_read_u16 v9, v9 offset:45056
	s_waitcnt lgkmcnt(0)
	v_lshlrev_b32_e32 v9, 16, v9
	v_mul_f32_e32 v9, v3, v9
	v_cvt_pk_bf16_f32 v3, v5, v6
	v_cvt_pk_bf16_f32 v5, v1, v9
	v_lshl_add_u32 v1, s54, 4, v113
	ds_write_b128 v1, v[2:5] offset:18432
	s_cbranch_vccnz .LBB0_246
	v_mul_f32_e32 v0, 0x3fb8aa3b, v0
	v_exp_f32_e32 v2, v0
	s_lshl_b64 s[56:57], s[6:7], 8
	v_lshl_add_u64 v[0:1], v[62:63], 0, s[56:57]
	global_store_dword v[0:1], v2, off
